# v47 + attention step loops: m0 wait state filled by the address add (s_nop dropped), raise flag kept as cmp mask, redundant condition masks and +3 add dropped (~7 fewer instrs per tile-step)
# baseline (speedup 1.0000x reference)
.LBB0_781:
	s_cmp_lt_i32 s30, s71
	s_cselect_b64 s[4:5], -1, 0
	s_cbranch_scc0 .Lattn_head_rare_m0
	s_waitcnt vmcnt(3) lgkmcnt(0)
	s_barrier
.LBB0_785:
	s_add_i32 s22, s30, 1
	s_cmp_lt_i32 s22, s71
	s_cselect_b64 s[94:95], -1, 0
	v_lshl_add_u64 v[192:193], v[188:189], 0, s[92:93]
	s_cbranch_scc0 .LBB0_787
	s_mul_hi_u32 s28, s31, 0xaaaaaaab
	s_lshr_b32 s28, s28, 1
	s_mulk_i32 s28, 0x6000
	s_sub_i32 s28, s56, s28
	s_add_i32 s28, s14, s28
	s_addk_i32 s28, 0xa000
	s_mov_b32 m0, s28
	v_lshl_add_u64 v[114:115], v[192:193], 0, s[38:39]
	global_load_lds_dwordx4 v[114:115], off
.LBB0_787:
	s_andn2_b64 vcc, exec, s[4:5]
	v_lshl_add_u64 v[194:195], v[190:191], 0, s[92:93]
	s_cbranch_vccnz .LBB0_789
	s_add_i32 s4, s14, 0xffffe000
	s_and_b32 s4, s4, 0x6000
	s_add_i32 s5, s4, s54
	s_add_i32 s4, s4, s55
	s_mov_b32 m0, s4
	v_lshl_add_u64 v[114:115], v[194:195], 0, s[40:41]
	global_load_lds_dwordx4 v[114:115], off
	s_mov_b32 m0, s5
	v_lshl_add_u64 v[116:117], v[194:195], 0, s[42:43]
	global_load_lds_dwordx4 v[116:117], off
.LBB0_789:
	s_mul_hi_u32 s4, s61, 0xaaaaaaab
	s_lshr_b32 s50, s4, 1
	s_mul_i32 s4, s50, 0xffffa000
	s_add_i32 s4, s14, s4
	s_and_b32 s51, s14, 0x6000
	v_add_u32_e32 v217, s4, v214
	v_add_u32_e32 v216, s51, v147
	v_add_u32_e32 v217, 0xffffc000, v217
	ds_read_b64_tr_b16 v[118:119], v216 offset:24576
	ds_read_b64_tr_b16 v[120:121], v216 offset:25088
	ds_read_b64_tr_b16 v[122:123], v216 offset:28672
	ds_read_b64_tr_b16 v[124:125], v216 offset:29184
	ds_read_b128 v[114:117], v217
	s_waitcnt lgkmcnt(3)
	v_mfma_f32_32x32x16_bf16 v[18:33], v[164:167], v[118:121], v[18:33]
	ds_read_b64_tr_b16 v[126:127], v216 offset:57344
	ds_read_b64_tr_b16 v[128:129], v216 offset:57856
	s_waitcnt lgkmcnt(3)
	v_mfma_f32_32x32x16_bf16 v[50:65], v[164:167], v[122:125], v[50:65]
	ds_read_b64_tr_b16 v[130:131], v216 offset:61440
	ds_read_b64_tr_b16 v[132:133], v216 offset:61952
	s_waitcnt lgkmcnt(2)
	v_mfma_f32_32x32x16_bf16 v[34:49], v[164:167], v[126:129], v[34:49]
	ds_read_b64_tr_b16 v[118:119], v216 offset:25600
	ds_read_b64_tr_b16 v[120:121], v216 offset:26112
	s_waitcnt lgkmcnt(2)
	v_mfma_f32_32x32x16_bf16 v[2:17], v[164:167], v[130:133], v[2:17]
	ds_read_b64_tr_b16 v[180:181], v216 offset:29696
	ds_read_b64_tr_b16 v[182:183], v216 offset:30208
	v_max_f32_e32 v122, v98, v99
	v_max3_f32 v123, v100, v101, v67
	v_max3_f32 v122, v122, v66, v68
	v_max3_f32 v122, v122, v69, v102
	v_max3_f32 v123, v123, v104, v105
	v_max3_f32 v122, v122, v103, v70
	v_max3_f32 v123, v123, v72, v73
	v_max3_f32 v122, v122, v71, v106
	v_max3_f32 v123, v123, v108, v109
	v_max3_f32 v122, v122, v107, v74
	v_max3_f32 v123, v123, v76, v77
	v_max3_f32 v122, v122, v75, v110
	v_max3_f32 v123, v123, v112, v113
	v_max3_f32 v122, v122, v111, v78
	v_max3_f32 v123, v123, v80, v81
	v_max3_f32 v122, v122, v79, v123
	v_mov_b32_e32 v123, v122
	s_nop 1
	v_permlane32_swap_b32_e32 v122, v123
	v_max_f32_e32 v122, v122, v123
	v_cmp_lt_f32_e32 vcc, s15, v122
	s_mov_b64 s[4:5], vcc
	s_cbranch_vccnz .Lattn_rare_m0_a1
.LBB0_793:
	v_exp_f32_e32 v164, v98
	v_mfma_f32_32x32x16_bf16 v[130:145], v[114:117], v[148:151], v[82:97]
	v_exp_f32_e32 v165, v99
	v_exp_f32_e32 v230, v100
	ds_read_b64_tr_b16 v[218:219], v216 offset:58368
	ds_read_b64_tr_b16 v[220:221], v216 offset:58880
	v_exp_f32_e32 v231, v101
	ds_read_b128 v[222:225], v217 offset:512
	s_waitcnt lgkmcnt(5)
	v_mfma_f32_32x32x16_bf16 v[18:33], v[168:171], v[118:121], v[18:33]
	v_add_f32_e32 v98, v165, v164
	v_add_f32_e32 v98, v230, v98
	v_add_f32_e32 v232, v231, v98
	ds_read_b64_tr_b16 v[98:99], v216 offset:62464
	ds_read_b64_tr_b16 v[100:101], v216 offset:62976
	ds_read_b128 v[226:229], v217 offset:2048
	v_exp_f32_e32 v233, v102
	s_waitcnt lgkmcnt(3)
	v_mfma_f32_32x32x16_bf16 v[114:129], v[222:225], v[148:151], v[82:97]
	v_exp_f32_e32 v222, v103
	v_exp_f32_e32 v223, v104
	v_exp_f32_e32 v224, v105
	v_add_f32_e32 v102, v233, v232
	v_add_f32_e32 v102, v222, v102
	v_add_f32_e32 v102, v223, v102
	v_add_f32_e32 v225, v224, v102
	v_mfma_f32_32x32x16_bf16 v[50:65], v[168:171], v[180:183], v[50:65]
	v_exp_f32_e32 v232, v106
	s_waitcnt lgkmcnt(0)
	v_mfma_f32_32x32x16_bf16 v[130:145], v[226:229], v[152:155], v[130:145]
	v_exp_f32_e32 v234, v107
	v_exp_f32_e32 v226, v108
	ds_read_b64_tr_b16 v[102:103], v216 offset:26624
	ds_read_b64_tr_b16 v[104:105], v216 offset:27136
	v_exp_f32_e32 v227, v109
	ds_read_b128 v[180:183], v217 offset:2560
	v_add_f32_e32 v106, v232, v225
	v_mfma_f32_32x32x16_bf16 v[34:49], v[168:171], v[218:221], v[34:49]
	v_add_f32_e32 v106, v234, v106
	v_add_f32_e32 v106, v226, v106
	v_add_f32_e32 v225, v227, v106
	v_cvt_pk_bf16_f32 v164, v164, v165
	v_cvt_pk_bf16_f32 v165, v230, v231
	v_exp_f32_e32 v228, v110
	s_waitcnt lgkmcnt(0)
	v_mfma_f32_32x32x16_bf16 v[114:129], v[180:183], v[152:155], v[114:129]
	v_exp_f32_e32 v229, v111
	v_exp_f32_e32 v180, v112
	ds_read_b64_tr_b16 v[106:107], v216 offset:30720
	ds_read_b64_tr_b16 v[108:109], v216 offset:31232
	v_exp_f32_e32 v181, v113
	ds_read_b128 v[218:221], v217 offset:4096
	v_add_f32_e32 v110, v228, v225
	v_mfma_f32_32x32x16_bf16 v[2:17], v[168:171], v[98:101], v[2:17]
	v_add_f32_e32 v110, v229, v110
	v_add_f32_e32 v110, v180, v110
	v_add_f32_e32 v182, v181, v110
	v_cvt_pk_bf16_f32 v166, v233, v222
	v_cvt_pk_bf16_f32 v167, v223, v224
	s_waitcnt lgkmcnt(0)
	v_mfma_f32_32x32x16_bf16 v[130:145], v[218:221], v[156:159], v[130:145]
	v_exp_f32_e32 v183, v66
	ds_read_b64_tr_b16 v[98:99], v216 offset:59392
	ds_read_b64_tr_b16 v[100:101], v216 offset:59904
	v_exp_f32_e32 v222, v67
	ds_read_b128 v[110:113], v217 offset:4608
	v_add_f32_e32 v66, v183, v182
	v_cvt_pk_bf16_f32 v168, v232, v234
	v_mfma_f32_32x32x16_bf16 v[18:33], v[172:175], v[102:105], v[18:33]
	v_add_f32_e32 v66, v222, v66
	v_cvt_pk_bf16_f32 v169, v226, v227
	v_mfma_f32_32x32x16_bf16 v[50:65], v[172:175], v[106:109], v[50:65]
	v_exp_f32_e32 v182, v68
	ds_read_b64_tr_b16 v[102:103], v216 offset:63488
	ds_read_b64_tr_b16 v[104:105], v216 offset:64000
	v_exp_f32_e32 v218, v69
	v_cvt_pk_bf16_f32 v170, v228, v229
	v_add_f32_e32 v66, v182, v66
	v_cvt_pk_bf16_f32 v171, v180, v181
	v_add_f32_e32 v219, v218, v66
	s_waitcnt lgkmcnt(2)
	v_mfma_f32_32x32x16_bf16 v[114:129], v[110:113], v[156:159], v[114:129]
	v_exp_f32_e32 v110, v70
	ds_read_b64_tr_b16 v[66:67], v216 offset:27648
	ds_read_b64_tr_b16 v[68:69], v216 offset:28160
	v_exp_f32_e32 v111, v71
	ds_read_b128 v[106:109], v217 offset:6144
	v_add_f32_e32 v70, v110, v219
	v_add_f32_e32 v70, v111, v70
	v_mfma_f32_32x32x16_bf16 v[34:49], v[172:175], v[98:101], v[34:49]
	s_waitcnt lgkmcnt(3)
	v_mfma_f32_32x32x16_bf16 v[2:17], v[172:175], v[102:105], v[2:17]
	v_exp_f32_e32 v112, v72
	ds_read_b64_tr_b16 v[98:99], v216 offset:31744
	ds_read_b64_tr_b16 v[100:101], v216 offset:32256
	v_exp_f32_e32 v113, v73
	v_add_f32_e32 v70, v112, v70
	v_add_f32_e32 v172, v113, v70
	s_waitcnt lgkmcnt(2)
	v_mfma_f32_32x32x16_bf16 v[130:145], v[106:109], v[160:163], v[130:145]
	v_exp_f32_e32 v74, v74
	ds_read_b64_tr_b16 v[70:71], v216 offset:60416
	ds_read_b64_tr_b16 v[72:73], v216 offset:60928
	v_exp_f32_e32 v75, v75
	ds_read_b128 v[102:105], v217 offset:6656
	v_add_f32_e32 v106, v74, v172
	v_cvt_pk_bf16_f32 v172, v183, v222
	v_mfma_f32_32x32x16_bf16 v[18:33], v[176:179], v[66:69], v[18:33]
	v_add_f32_e32 v106, v75, v106
	v_cvt_pk_bf16_f32 v173, v182, v218
	s_waitcnt lgkmcnt(3)
	v_mfma_f32_32x32x16_bf16 v[50:65], v[176:179], v[98:101], v[50:65]
	v_exp_f32_e32 v76, v76
	v_exp_f32_e32 v77, v77
	ds_read_b64_tr_b16 v[66:67], v216 offset:64512
	ds_read_b64_tr_b16 v[68:69], v216 offset:65024
	v_cvt_pk_bf16_f32 v174, v110, v111
	v_add_f32_e32 v106, v76, v106
	v_add_f32_e32 v106, v77, v106
	v_cvt_pk_bf16_f32 v175, v112, v113
	s_waitcnt lgkmcnt(2)
	v_mfma_f32_32x32x16_bf16 v[114:129], v[102:105], v[160:163], v[114:129]
	v_exp_f32_e32 v78, v78
	v_exp_f32_e32 v79, v79
	v_add_f32_e32 v98, v78, v106
	v_add_f32_e32 v98, v79, v98
	v_mfma_f32_32x32x16_bf16 v[34:49], v[176:179], v[70:73], v[34:49]
	s_waitcnt lgkmcnt(0)
	v_mfma_f32_32x32x16_bf16 v[2:17], v[176:179], v[66:69], v[2:17]
	v_exp_f32_e32 v80, v80
	v_exp_f32_e32 v81, v81
	v_add_f32_e32 v66, v80, v98
	v_add_f32_e32 v66, v81, v66
	s_cmp_lg_u64 s[4:5], 0
	s_cbranch_scc1 .Lattn_rare_m0_b2
.LBB0_795:
	s_add_i32 s28, s33, s30
	s_cmp_lt_i32 s28, -3
	s_cbranch_scc0 .Lattn_rare_m0_c3
.LBB0_797:
	s_andn2_b64 vcc, exec, s[94:95]
	s_cbranch_vccnz .LBB0_812
	s_waitcnt vmcnt(3) lgkmcnt(0)
	s_barrier
	s_add_i32 s29, s30, 2
	s_cmp_ge_i32 s29, s71
	s_cbranch_scc1 .LBB0_800
	s_mulk_i32 s50, 0x6000
	s_sub_i32 s4, s56, s50
	s_add_i32 s4, s14, s4
	s_addk_i32 s4, 0xc000
	s_mov_b32 m0, s4
	v_lshl_add_u64 v[68:69], v[192:193], 0, s[44:45]
	global_load_lds_dwordx4 v[68:69], off
	s_andn2_b64 vcc, exec, s[94:95]
	s_cbranch_vccnz .LBB0_802
.LBB0_801:
	s_add_i32 s5, s51, s55
	s_mov_b32 m0, s5
	v_lshl_add_u64 v[68:69], v[194:195], 0, s[46:47]
	global_load_lds_dwordx4 v[68:69], off
	s_add_i32 s4, s51, s54
	s_mov_b32 m0, s4
	v_lshl_add_u64 v[70:71], v[194:195], 0, s[48:49]
	global_load_lds_dwordx4 v[70:71], off
.LBB0_802:
	s_mul_hi_u32 s4, s30, 0xaaaaaaab
	s_lshr_b32 s4, s4, 1
	s_mulk_i32 s4, 0xa000
	s_add_i32 s5, s14, 0xffffa000
	s_add_i32 s4, s14, s4
	s_and_b32 s5, s5, 0x6000
	v_add_u32_e32 v194, s4, v214
	v_add_f32_e32 v192, v213, v66
	v_add_u32_e32 v193, s5, v147
	v_add_u32_e32 v194, 0xffffe000, v194
	ds_read_b64_tr_b16 v[70:71], v193 offset:24576
	ds_read_b64_tr_b16 v[72:73], v193 offset:25088
	ds_read_b64_tr_b16 v[98:99], v193 offset:28672
	ds_read_b64_tr_b16 v[100:101], v193 offset:29184
	ds_read_b128 v[66:69], v194
	s_waitcnt lgkmcnt(3)
	v_mfma_f32_32x32x16_bf16 v[18:33], v[164:167], v[70:73], v[18:33]
	ds_read_b64_tr_b16 v[102:103], v193 offset:57344
	ds_read_b64_tr_b16 v[104:105], v193 offset:57856
	s_waitcnt lgkmcnt(3)
	v_mfma_f32_32x32x16_bf16 v[50:65], v[164:167], v[98:101], v[50:65]
	ds_read_b64_tr_b16 v[106:107], v193 offset:61440
	ds_read_b64_tr_b16 v[108:109], v193 offset:61952
	s_waitcnt lgkmcnt(2)
	v_mfma_f32_32x32x16_bf16 v[34:49], v[164:167], v[102:105], v[34:49]
	ds_read_b64_tr_b16 v[70:71], v193 offset:25600
	ds_read_b64_tr_b16 v[72:73], v193 offset:26112
	s_waitcnt lgkmcnt(2)
	v_mfma_f32_32x32x16_bf16 v[2:17], v[164:167], v[106:109], v[2:17]
	ds_read_b64_tr_b16 v[180:181], v193 offset:29696
	ds_read_b64_tr_b16 v[182:183], v193 offset:30208
	v_max_f32_e32 v98, v130, v131
	v_max3_f32 v99, v132, v133, v115
	v_max3_f32 v98, v98, v114, v116
	v_max3_f32 v98, v98, v117, v134
	v_max3_f32 v99, v99, v136, v137
	v_max3_f32 v98, v98, v135, v118
	v_max3_f32 v99, v99, v120, v121
	v_max3_f32 v98, v98, v119, v138
	v_max3_f32 v99, v99, v140, v141
	v_max3_f32 v98, v98, v139, v122
	v_max3_f32 v99, v99, v124, v125
	v_max3_f32 v98, v98, v123, v142
	v_max3_f32 v99, v99, v144, v145
	v_max3_f32 v98, v98, v143, v126
	v_max3_f32 v99, v99, v128, v129
	v_max3_f32 v98, v98, v127, v99
	v_mov_b32_e32 v99, v98
	s_nop 1
	v_permlane32_swap_b32_e32 v98, v99
	v_max_f32_e32 v98, v98, v99
	v_cmp_lt_f32_e32 vcc, s15, v98
	s_mov_b64 s[4:5], vcc
	s_cbranch_vccnz .Lattn_rare_m0_a4
.LBB0_806:
	v_cvt_pk_bf16_f32 v176, v74, v75
	v_cvt_pk_bf16_f32 v177, v76, v77
	v_cvt_pk_bf16_f32 v178, v78, v79
	v_cvt_pk_bf16_f32 v179, v80, v81
	v_exp_f32_e32 v164, v130
	v_mfma_f32_32x32x16_bf16 v[98:113], v[66:69], v[148:151], v[82:97]
	v_exp_f32_e32 v165, v131
	v_exp_f32_e32 v195, v132
	ds_read_b64_tr_b16 v[216:217], v193 offset:58368
	ds_read_b64_tr_b16 v[218:219], v193 offset:58880
	v_exp_f32_e32 v213, v133
	ds_read_b128 v[220:223], v194 offset:512
	s_waitcnt lgkmcnt(5)
	v_mfma_f32_32x32x16_bf16 v[18:33], v[168:171], v[70:73], v[18:33]
	v_add_f32_e32 v66, v165, v164
	v_add_f32_e32 v66, v195, v66
	v_add_f32_e32 v228, v213, v66
	ds_read_b64_tr_b16 v[130:131], v193 offset:62464
	ds_read_b64_tr_b16 v[132:133], v193 offset:62976
	ds_read_b128 v[224:227], v194 offset:2048
	v_exp_f32_e32 v229, v134
	s_waitcnt lgkmcnt(3)
	v_mfma_f32_32x32x16_bf16 v[66:81], v[220:223], v[148:151], v[82:97]
	v_exp_f32_e32 v220, v135
	v_exp_f32_e32 v221, v136
	v_exp_f32_e32 v222, v137
	v_add_f32_e32 v134, v229, v228
	v_add_f32_e32 v134, v220, v134
	v_add_f32_e32 v134, v221, v134
	v_add_f32_e32 v223, v222, v134
	v_mfma_f32_32x32x16_bf16 v[50:65], v[168:171], v[180:183], v[50:65]
	v_exp_f32_e32 v228, v138
	s_waitcnt lgkmcnt(0)
	v_mfma_f32_32x32x16_bf16 v[98:113], v[224:227], v[152:155], v[98:113]
	v_exp_f32_e32 v230, v139
	v_exp_f32_e32 v224, v140
	ds_read_b64_tr_b16 v[134:135], v193 offset:26624
	ds_read_b64_tr_b16 v[136:137], v193 offset:27136
	v_exp_f32_e32 v225, v141
	ds_read_b128 v[180:183], v194 offset:2560
	v_add_f32_e32 v138, v228, v223
	v_mfma_f32_32x32x16_bf16 v[34:49], v[168:171], v[216:219], v[34:49]
	v_add_f32_e32 v138, v230, v138
	v_add_f32_e32 v138, v224, v138
	v_add_f32_e32 v223, v225, v138
	v_cvt_pk_bf16_f32 v164, v164, v165
	v_cvt_pk_bf16_f32 v165, v195, v213
	v_exp_f32_e32 v195, v142
	s_waitcnt lgkmcnt(0)
	v_mfma_f32_32x32x16_bf16 v[66:81], v[180:183], v[152:155], v[66:81]
	v_exp_f32_e32 v213, v143
	v_exp_f32_e32 v180, v144
	ds_read_b64_tr_b16 v[138:139], v193 offset:30720
	ds_read_b64_tr_b16 v[140:141], v193 offset:31232
	v_exp_f32_e32 v181, v145
	ds_read_b128 v[216:219], v194 offset:4096
	v_add_f32_e32 v142, v195, v223
	v_mfma_f32_32x32x16_bf16 v[2:17], v[168:171], v[130:133], v[2:17]
	v_add_f32_e32 v142, v213, v142
	v_add_f32_e32 v142, v180, v142
	v_add_f32_e32 v182, v181, v142
	v_cvt_pk_bf16_f32 v166, v229, v220
	v_cvt_pk_bf16_f32 v167, v221, v222
	s_waitcnt lgkmcnt(0)
	v_mfma_f32_32x32x16_bf16 v[98:113], v[216:219], v[156:159], v[98:113]
	v_exp_f32_e32 v183, v114
	ds_read_b64_tr_b16 v[130:131], v193 offset:59392
	ds_read_b64_tr_b16 v[132:133], v193 offset:59904
	v_exp_f32_e32 v220, v115
	ds_read_b128 v[142:145], v194 offset:4608
	v_add_f32_e32 v114, v183, v182
	v_cvt_pk_bf16_f32 v168, v228, v230
	v_mfma_f32_32x32x16_bf16 v[18:33], v[172:175], v[134:137], v[18:33]
	v_add_f32_e32 v114, v220, v114
	v_cvt_pk_bf16_f32 v169, v224, v225
	v_mfma_f32_32x32x16_bf16 v[50:65], v[172:175], v[138:141], v[50:65]
	v_exp_f32_e32 v182, v116
	ds_read_b64_tr_b16 v[134:135], v193 offset:63488
	ds_read_b64_tr_b16 v[136:137], v193 offset:64000
	v_exp_f32_e32 v216, v117
	v_cvt_pk_bf16_f32 v170, v195, v213
	v_add_f32_e32 v114, v182, v114
	v_cvt_pk_bf16_f32 v171, v180, v181
	v_add_f32_e32 v114, v216, v114
	s_waitcnt lgkmcnt(2)
	v_mfma_f32_32x32x16_bf16 v[66:81], v[142:145], v[156:159], v[66:81]
	v_exp_f32_e32 v142, v118
	ds_read_b64_tr_b16 v[138:139], v193 offset:27648
	ds_read_b64_tr_b16 v[140:141], v193 offset:28160
	v_exp_f32_e32 v143, v119
	ds_read_b128 v[116:119], v194 offset:6144
	v_add_f32_e32 v114, v142, v114
	v_add_f32_e32 v114, v143, v114
	v_mfma_f32_32x32x16_bf16 v[34:49], v[172:175], v[130:133], v[34:49]
	s_waitcnt lgkmcnt(3)
	v_mfma_f32_32x32x16_bf16 v[2:17], v[172:175], v[134:137], v[2:17]
	v_exp_f32_e32 v144, v120
	ds_read_b64_tr_b16 v[130:131], v193 offset:31744
	ds_read_b64_tr_b16 v[132:133], v193 offset:32256
	v_exp_f32_e32 v145, v121
	v_add_f32_e32 v114, v144, v114
	v_add_f32_e32 v172, v145, v114
	s_waitcnt lgkmcnt(2)
	v_mfma_f32_32x32x16_bf16 v[98:113], v[116:119], v[160:163], v[98:113]
	v_exp_f32_e32 v114, v122
	ds_read_b64_tr_b16 v[134:135], v193 offset:60416
	ds_read_b64_tr_b16 v[136:137], v193 offset:60928
	v_exp_f32_e32 v115, v123
	ds_read_b128 v[118:121], v194 offset:6656
	v_add_f32_e32 v116, v114, v172
	v_cvt_pk_bf16_f32 v172, v183, v220
	v_mfma_f32_32x32x16_bf16 v[18:33], v[176:179], v[138:141], v[18:33]
	v_add_f32_e32 v180, v115, v116
	v_cvt_pk_bf16_f32 v173, v182, v216
	s_waitcnt lgkmcnt(3)
	v_mfma_f32_32x32x16_bf16 v[50:65], v[176:179], v[130:133], v[50:65]
	v_exp_f32_e32 v116, v124
	v_exp_f32_e32 v117, v125
	ds_read_b64_tr_b16 v[122:123], v193 offset:64512
	ds_read_b64_tr_b16 v[124:125], v193 offset:65024
	v_cvt_pk_bf16_f32 v174, v142, v143
	v_add_f32_e32 v138, v116, v180
	v_add_f32_e32 v138, v117, v138
	v_cvt_pk_bf16_f32 v175, v144, v145
	s_waitcnt lgkmcnt(2)
	v_mfma_f32_32x32x16_bf16 v[66:81], v[118:121], v[160:163], v[66:81]
	v_exp_f32_e32 v118, v126
	v_exp_f32_e32 v119, v127
	v_add_f32_e32 v120, v118, v138
	v_add_f32_e32 v126, v119, v120
	v_mfma_f32_32x32x16_bf16 v[34:49], v[176:179], v[134:137], v[34:49]
	s_waitcnt lgkmcnt(0)
	v_mfma_f32_32x32x16_bf16 v[2:17], v[176:179], v[122:125], v[2:17]
	v_exp_f32_e32 v120, v128
	v_exp_f32_e32 v121, v129
	v_add_f32_e32 v122, v120, v126
	v_add_f32_e32 v122, v121, v122
	s_cmp_lg_u64 s[4:5], 0
	s_cbranch_scc1 .Lattn_rare_m0_b5

.LBB0_812:
	s_mov_b64 s[4:5], -1
	s_cmp_lt_i32 s30, s71
	s_cbranch_scc1 .LBB0_814
	s_waitcnt vmcnt(0) lgkmcnt(0)
	s_barrier
	s_mov_b64 s[4:5], 0

.LBB0_818:
	s_mulk_i32 s50, 0x6000
	s_sub_i32 s4, s56, s50
	s_add_i32 s4, s14, s4
	s_addk_i32 s4, 0xc000
	s_mov_b32 m0, s4
	v_lshl_add_u64 v[68:69], v[192:193], 0, s[44:45]
	global_load_lds_dwordx4 v[68:69], off
	s_andn2_b64 vcc, exec, s[94:95]
	s_cbranch_vccz .LBB0_801
	s_branch .LBB0_802

.LBB0_853:
	s_add_i32 s22, s30, 1
	s_cmp_lt_i32 s22, s71
	s_cselect_b64 s[76:77], -1, 0
	v_lshl_add_u64 v[192:193], v[188:189], 0, s[74:75]
	s_cbranch_scc0 .LBB0_855
	s_mul_hi_u32 s28, s31, 0xaaaaaaab
	s_lshr_b32 s28, s28, 1
	s_mulk_i32 s28, 0x6000
	s_sub_i32 s28, s25, s28
	s_add_i32 s28, s14, s28
	s_addk_i32 s28, 0xa000
	s_mov_b32 m0, s28
	v_lshl_add_u64 v[114:115], v[192:193], 0, s[38:39]
	global_load_lds_dwordx4 v[114:115], off
.LBB0_855:
	s_andn2_b64 vcc, exec, s[4:5]
	v_lshl_add_u64 v[194:195], v[190:191], 0, s[74:75]
	s_cbranch_vccnz .LBB0_857
	s_add_i32 s4, s14, 0xffffe000
	s_and_b32 s4, s4, 0x6000
	s_add_i32 s5, s4, s54
	s_add_i32 s4, s4, s55
	s_mov_b32 m0, s4
	v_lshl_add_u64 v[114:115], v[194:195], 0, s[40:41]
	global_load_lds_dwordx4 v[114:115], off
	s_mov_b32 m0, s5
	v_lshl_add_u64 v[116:117], v[194:195], 0, s[42:43]
	global_load_lds_dwordx4 v[116:117], off
.LBB0_857:
	s_mul_hi_u32 s4, s56, 0xaaaaaaab
	s_lshr_b32 s50, s4, 1
	s_mul_i32 s4, s50, 0xffffa000
	s_add_i32 s4, s14, s4
	s_and_b32 s51, s14, 0x6000
	v_add_u32_e32 v216, s4, v187
	v_add_u32_e32 v215, s51, v209
	v_add_u32_e32 v216, 0xffffc000, v216
	ds_read_b64_tr_b16 v[118:119], v215 offset:24576
	ds_read_b64_tr_b16 v[120:121], v215 offset:25088
	ds_read_b64_tr_b16 v[122:123], v215 offset:28672
	ds_read_b64_tr_b16 v[124:125], v215 offset:29184
	ds_read_b128 v[114:117], v216
	s_waitcnt lgkmcnt(3)
	v_mfma_f32_32x32x16_bf16 v[18:33], v[164:167], v[118:121], v[18:33]
	ds_read_b64_tr_b16 v[126:127], v215 offset:57344
	ds_read_b64_tr_b16 v[128:129], v215 offset:57856
	s_waitcnt lgkmcnt(3)
	v_mfma_f32_32x32x16_bf16 v[50:65], v[164:167], v[122:125], v[50:65]
	ds_read_b64_tr_b16 v[130:131], v215 offset:61440
	ds_read_b64_tr_b16 v[132:133], v215 offset:61952
	s_waitcnt lgkmcnt(2)
	v_mfma_f32_32x32x16_bf16 v[34:49], v[164:167], v[126:129], v[34:49]
	ds_read_b64_tr_b16 v[118:119], v215 offset:25600
	ds_read_b64_tr_b16 v[120:121], v215 offset:26112
	s_waitcnt lgkmcnt(2)
	v_mfma_f32_32x32x16_bf16 v[2:17], v[164:167], v[130:133], v[2:17]
	ds_read_b64_tr_b16 v[180:181], v215 offset:29696
	ds_read_b64_tr_b16 v[182:183], v215 offset:30208
	v_max_f32_e32 v122, v98, v99
	v_max3_f32 v123, v100, v101, v67
	v_max3_f32 v122, v122, v66, v68
	v_max3_f32 v122, v122, v69, v102
	v_max3_f32 v123, v123, v104, v105
	v_max3_f32 v122, v122, v103, v70
	v_max3_f32 v123, v123, v72, v73
	v_max3_f32 v122, v122, v71, v106
	v_max3_f32 v123, v123, v108, v109
	v_max3_f32 v122, v122, v107, v74
	v_max3_f32 v123, v123, v76, v77
	v_max3_f32 v122, v122, v75, v110
	v_max3_f32 v123, v123, v112, v113
	v_max3_f32 v122, v122, v111, v78
	v_max3_f32 v123, v123, v80, v81
	v_max3_f32 v122, v122, v79, v123
	v_mov_b32_e32 v123, v122
	s_nop 1
	v_permlane32_swap_b32_e32 v122, v123
	v_max_f32_e32 v122, v122, v123
	v_cmp_lt_f32_e32 vcc, s15, v122
	s_mov_b64 s[4:5], vcc
	s_cbranch_vccnz .Lattn_rare_m1_a1
.LBB0_861:
	v_exp_f32_e32 v164, v98
	v_mfma_f32_32x32x16_bf16 v[130:145], v[114:117], v[148:151], v[82:97]
	v_exp_f32_e32 v165, v99
	v_exp_f32_e32 v217, v100
	ds_read_b64_tr_b16 v[218:219], v215 offset:58368
	ds_read_b64_tr_b16 v[220:221], v215 offset:58880
	v_exp_f32_e32 v230, v101
	ds_read_b128 v[222:225], v216 offset:512
	s_waitcnt lgkmcnt(5)
	v_mfma_f32_32x32x16_bf16 v[18:33], v[168:171], v[118:121], v[18:33]
	v_add_f32_e32 v98, v165, v164
	v_add_f32_e32 v98, v217, v98
	v_add_f32_e32 v231, v230, v98
	ds_read_b64_tr_b16 v[98:99], v215 offset:62464
	ds_read_b64_tr_b16 v[100:101], v215 offset:62976
	ds_read_b128 v[226:229], v216 offset:2048
	v_exp_f32_e32 v232, v102
	s_waitcnt lgkmcnt(3)
	v_mfma_f32_32x32x16_bf16 v[114:129], v[222:225], v[148:151], v[82:97]
	v_exp_f32_e32 v222, v103
	v_exp_f32_e32 v223, v104
	v_exp_f32_e32 v224, v105
	v_add_f32_e32 v102, v232, v231
	v_add_f32_e32 v102, v222, v102
	v_add_f32_e32 v102, v223, v102
	v_add_f32_e32 v225, v224, v102
	v_mfma_f32_32x32x16_bf16 v[50:65], v[168:171], v[180:183], v[50:65]
	v_exp_f32_e32 v231, v106
	s_waitcnt lgkmcnt(0)
	v_mfma_f32_32x32x16_bf16 v[130:145], v[226:229], v[152:155], v[130:145]
	v_exp_f32_e32 v233, v107
	v_exp_f32_e32 v226, v108
	ds_read_b64_tr_b16 v[102:103], v215 offset:26624
	ds_read_b64_tr_b16 v[104:105], v215 offset:27136
	v_exp_f32_e32 v227, v109
	ds_read_b128 v[180:183], v216 offset:2560
	v_add_f32_e32 v106, v231, v225
	v_mfma_f32_32x32x16_bf16 v[34:49], v[168:171], v[218:221], v[34:49]
	v_add_f32_e32 v106, v233, v106
	v_add_f32_e32 v106, v226, v106
	v_add_f32_e32 v225, v227, v106
	v_cvt_pk_bf16_f32 v164, v164, v165
	v_cvt_pk_bf16_f32 v165, v217, v230
	v_exp_f32_e32 v217, v110
	s_waitcnt lgkmcnt(0)
	v_mfma_f32_32x32x16_bf16 v[114:129], v[180:183], v[152:155], v[114:129]
	v_exp_f32_e32 v228, v111
	v_exp_f32_e32 v180, v112
	ds_read_b64_tr_b16 v[106:107], v215 offset:30720
	ds_read_b64_tr_b16 v[108:109], v215 offset:31232
	v_exp_f32_e32 v181, v113
	ds_read_b128 v[218:221], v216 offset:4096
	v_add_f32_e32 v110, v217, v225
	v_mfma_f32_32x32x16_bf16 v[2:17], v[168:171], v[98:101], v[2:17]
	v_add_f32_e32 v110, v228, v110
	v_add_f32_e32 v110, v180, v110
	v_add_f32_e32 v182, v181, v110
	v_cvt_pk_bf16_f32 v166, v232, v222
	v_cvt_pk_bf16_f32 v167, v223, v224
	s_waitcnt lgkmcnt(0)
	v_mfma_f32_32x32x16_bf16 v[130:145], v[218:221], v[156:159], v[130:145]
	v_exp_f32_e32 v183, v66
	ds_read_b64_tr_b16 v[98:99], v215 offset:59392
	ds_read_b64_tr_b16 v[100:101], v215 offset:59904
	v_exp_f32_e32 v222, v67
	ds_read_b128 v[110:113], v216 offset:4608
	v_add_f32_e32 v66, v183, v182
	v_cvt_pk_bf16_f32 v168, v231, v233
	v_mfma_f32_32x32x16_bf16 v[18:33], v[172:175], v[102:105], v[18:33]
	v_add_f32_e32 v66, v222, v66
	v_cvt_pk_bf16_f32 v169, v226, v227
	v_mfma_f32_32x32x16_bf16 v[50:65], v[172:175], v[106:109], v[50:65]
	v_exp_f32_e32 v182, v68
	ds_read_b64_tr_b16 v[102:103], v215 offset:63488
	ds_read_b64_tr_b16 v[104:105], v215 offset:64000
	v_exp_f32_e32 v218, v69
	v_cvt_pk_bf16_f32 v170, v217, v228
	v_add_f32_e32 v66, v182, v66
	v_cvt_pk_bf16_f32 v171, v180, v181
	v_add_f32_e32 v219, v218, v66
	s_waitcnt lgkmcnt(2)
	v_mfma_f32_32x32x16_bf16 v[114:129], v[110:113], v[156:159], v[114:129]
	v_exp_f32_e32 v110, v70
	ds_read_b64_tr_b16 v[66:67], v215 offset:27648
	ds_read_b64_tr_b16 v[68:69], v215 offset:28160
	v_exp_f32_e32 v111, v71
	ds_read_b128 v[106:109], v216 offset:6144
	v_add_f32_e32 v70, v110, v219
	v_add_f32_e32 v70, v111, v70
	v_mfma_f32_32x32x16_bf16 v[34:49], v[172:175], v[98:101], v[34:49]
	s_waitcnt lgkmcnt(3)
	v_mfma_f32_32x32x16_bf16 v[2:17], v[172:175], v[102:105], v[2:17]
	v_exp_f32_e32 v112, v72
	ds_read_b64_tr_b16 v[98:99], v215 offset:31744
	ds_read_b64_tr_b16 v[100:101], v215 offset:32256
	v_exp_f32_e32 v113, v73
	v_add_f32_e32 v70, v112, v70
	v_add_f32_e32 v172, v113, v70
	s_waitcnt lgkmcnt(2)
	v_mfma_f32_32x32x16_bf16 v[130:145], v[106:109], v[160:163], v[130:145]
	v_exp_f32_e32 v74, v74
	ds_read_b64_tr_b16 v[70:71], v215 offset:60416
	ds_read_b64_tr_b16 v[72:73], v215 offset:60928
	v_exp_f32_e32 v75, v75
	ds_read_b128 v[102:105], v216 offset:6656
	v_add_f32_e32 v106, v74, v172
	v_cvt_pk_bf16_f32 v172, v183, v222
	v_mfma_f32_32x32x16_bf16 v[18:33], v[176:179], v[66:69], v[18:33]
	v_add_f32_e32 v106, v75, v106
	v_cvt_pk_bf16_f32 v173, v182, v218
	s_waitcnt lgkmcnt(3)
	v_mfma_f32_32x32x16_bf16 v[50:65], v[176:179], v[98:101], v[50:65]
	v_exp_f32_e32 v76, v76
	v_exp_f32_e32 v77, v77
	ds_read_b64_tr_b16 v[66:67], v215 offset:64512
	ds_read_b64_tr_b16 v[68:69], v215 offset:65024
	v_cvt_pk_bf16_f32 v174, v110, v111
	v_add_f32_e32 v106, v76, v106
	v_add_f32_e32 v106, v77, v106
	v_cvt_pk_bf16_f32 v175, v112, v113
	s_waitcnt lgkmcnt(2)
	v_mfma_f32_32x32x16_bf16 v[114:129], v[102:105], v[160:163], v[114:129]
	v_exp_f32_e32 v78, v78
	v_exp_f32_e32 v79, v79
	v_add_f32_e32 v98, v78, v106
	v_add_f32_e32 v98, v79, v98
	v_mfma_f32_32x32x16_bf16 v[34:49], v[176:179], v[70:73], v[34:49]
	s_waitcnt lgkmcnt(0)
	v_mfma_f32_32x32x16_bf16 v[2:17], v[176:179], v[66:69], v[2:17]
	v_exp_f32_e32 v80, v80
	v_exp_f32_e32 v81, v81
	v_add_f32_e32 v66, v80, v98
	v_add_f32_e32 v66, v81, v66
	s_cmp_lg_u64 s[4:5], 0
	s_cbranch_scc1 .Lattn_rare_m1_b2

.LBB0_865:
	s_andn2_b64 vcc, exec, s[76:77]
	s_cbranch_vccnz .LBB0_880
	s_waitcnt vmcnt(3) lgkmcnt(0)
	s_barrier
	s_add_i32 s29, s30, 2
	s_cmp_ge_i32 s29, s71
	s_cbranch_scc1 .LBB0_868
	s_mulk_i32 s50, 0x6000
	s_sub_i32 s4, s25, s50
	s_add_i32 s4, s14, s4
	s_addk_i32 s4, 0xc000
	s_mov_b32 m0, s4
	v_lshl_add_u64 v[68:69], v[192:193], 0, s[44:45]
	global_load_lds_dwordx4 v[68:69], off
	s_andn2_b64 vcc, exec, s[76:77]
	s_cbranch_vccnz .LBB0_870

.LBB0_870:
	s_mul_hi_u32 s4, s30, 0xaaaaaaab
	s_lshr_b32 s4, s4, 1
	s_mulk_i32 s4, 0xa000
	s_add_i32 s5, s14, 0xffffa000
	s_add_i32 s4, s14, s4
	s_and_b32 s5, s5, 0x6000
	v_add_u32_e32 v194, s4, v187
	v_add_f32_e32 v192, v213, v66
	v_add_u32_e32 v193, s5, v209
	v_add_u32_e32 v194, 0xffffe000, v194
	ds_read_b64_tr_b16 v[70:71], v193 offset:24576
	ds_read_b64_tr_b16 v[72:73], v193 offset:25088
	ds_read_b64_tr_b16 v[98:99], v193 offset:28672
	ds_read_b64_tr_b16 v[100:101], v193 offset:29184
	ds_read_b128 v[66:69], v194
	s_waitcnt lgkmcnt(3)
	v_mfma_f32_32x32x16_bf16 v[18:33], v[164:167], v[70:73], v[18:33]
	ds_read_b64_tr_b16 v[102:103], v193 offset:57344
	ds_read_b64_tr_b16 v[104:105], v193 offset:57856
	s_waitcnt lgkmcnt(3)
	v_mfma_f32_32x32x16_bf16 v[50:65], v[164:167], v[98:101], v[50:65]
	ds_read_b64_tr_b16 v[106:107], v193 offset:61440
	ds_read_b64_tr_b16 v[108:109], v193 offset:61952
	s_waitcnt lgkmcnt(2)
	v_mfma_f32_32x32x16_bf16 v[34:49], v[164:167], v[102:105], v[34:49]
	ds_read_b64_tr_b16 v[70:71], v193 offset:25600
	ds_read_b64_tr_b16 v[72:73], v193 offset:26112
	s_waitcnt lgkmcnt(2)
	v_mfma_f32_32x32x16_bf16 v[2:17], v[164:167], v[106:109], v[2:17]
	ds_read_b64_tr_b16 v[180:181], v193 offset:29696
	ds_read_b64_tr_b16 v[182:183], v193 offset:30208
	v_max_f32_e32 v98, v130, v131
	v_max3_f32 v99, v132, v133, v115
	v_max3_f32 v98, v98, v114, v116
	v_max3_f32 v98, v98, v117, v134
	v_max3_f32 v99, v99, v136, v137
	v_max3_f32 v98, v98, v135, v118
	v_max3_f32 v99, v99, v120, v121
	v_max3_f32 v98, v98, v119, v138
	v_max3_f32 v99, v99, v140, v141
	v_max3_f32 v98, v98, v139, v122
	v_max3_f32 v99, v99, v124, v125
	v_max3_f32 v98, v98, v123, v142
	v_max3_f32 v99, v99, v144, v145
	v_max3_f32 v98, v98, v143, v126
	v_max3_f32 v99, v99, v128, v129
	v_max3_f32 v98, v98, v127, v99
	v_mov_b32_e32 v99, v98
	s_nop 1
	v_permlane32_swap_b32_e32 v98, v99
	v_max_f32_e32 v98, v98, v99
	v_cmp_lt_f32_e32 vcc, s15, v98
	s_mov_b64 s[4:5], vcc
	s_cbranch_vccnz .Lattn_rare_m1_a4
.LBB0_874:
	v_cvt_pk_bf16_f32 v176, v74, v75
	v_cvt_pk_bf16_f32 v177, v76, v77
	v_cvt_pk_bf16_f32 v178, v78, v79
	v_cvt_pk_bf16_f32 v179, v80, v81
	v_exp_f32_e32 v164, v130
	v_mfma_f32_32x32x16_bf16 v[98:113], v[66:69], v[148:151], v[82:97]
	v_exp_f32_e32 v165, v131
	v_exp_f32_e32 v195, v132
	ds_read_b64_tr_b16 v[216:217], v193 offset:58368
	ds_read_b64_tr_b16 v[218:219], v193 offset:58880
	v_exp_f32_e32 v213, v133
	ds_read_b128 v[220:223], v194 offset:512
	s_waitcnt lgkmcnt(5)
	v_mfma_f32_32x32x16_bf16 v[18:33], v[168:171], v[70:73], v[18:33]
	v_add_f32_e32 v66, v165, v164
	v_add_f32_e32 v66, v195, v66
	v_add_f32_e32 v215, v213, v66
	ds_read_b64_tr_b16 v[130:131], v193 offset:62464
	ds_read_b64_tr_b16 v[132:133], v193 offset:62976
	ds_read_b128 v[224:227], v194 offset:2048
	v_exp_f32_e32 v228, v134
	s_waitcnt lgkmcnt(3)
	v_mfma_f32_32x32x16_bf16 v[66:81], v[220:223], v[148:151], v[82:97]
	v_exp_f32_e32 v220, v135
	v_exp_f32_e32 v221, v136
	v_exp_f32_e32 v222, v137
	v_add_f32_e32 v134, v228, v215
	v_add_f32_e32 v134, v220, v134
	v_add_f32_e32 v134, v221, v134
	v_add_f32_e32 v215, v222, v134
	v_mfma_f32_32x32x16_bf16 v[50:65], v[168:171], v[180:183], v[50:65]
	v_exp_f32_e32 v223, v138
	s_waitcnt lgkmcnt(0)
	v_mfma_f32_32x32x16_bf16 v[98:113], v[224:227], v[152:155], v[98:113]
	v_exp_f32_e32 v229, v139
	v_exp_f32_e32 v224, v140
	ds_read_b64_tr_b16 v[134:135], v193 offset:26624
	ds_read_b64_tr_b16 v[136:137], v193 offset:27136
	v_exp_f32_e32 v225, v141
	ds_read_b128 v[180:183], v194 offset:2560
	v_add_f32_e32 v138, v223, v215
	v_mfma_f32_32x32x16_bf16 v[34:49], v[168:171], v[216:219], v[34:49]
	v_add_f32_e32 v138, v229, v138
	v_add_f32_e32 v138, v224, v138
	v_add_f32_e32 v215, v225, v138
	v_cvt_pk_bf16_f32 v164, v164, v165
	v_cvt_pk_bf16_f32 v165, v195, v213
	v_exp_f32_e32 v195, v142
	s_waitcnt lgkmcnt(0)
	v_mfma_f32_32x32x16_bf16 v[66:81], v[180:183], v[152:155], v[66:81]
	v_exp_f32_e32 v213, v143
	v_exp_f32_e32 v180, v144
	ds_read_b64_tr_b16 v[138:139], v193 offset:30720
	ds_read_b64_tr_b16 v[140:141], v193 offset:31232
	v_exp_f32_e32 v181, v145
	ds_read_b128 v[216:219], v194 offset:4096
	v_add_f32_e32 v142, v195, v215
	v_mfma_f32_32x32x16_bf16 v[2:17], v[168:171], v[130:133], v[2:17]
	v_add_f32_e32 v142, v213, v142
	v_add_f32_e32 v142, v180, v142
	v_add_f32_e32 v182, v181, v142
	v_cvt_pk_bf16_f32 v166, v228, v220
	v_cvt_pk_bf16_f32 v167, v221, v222
	s_waitcnt lgkmcnt(0)
	v_mfma_f32_32x32x16_bf16 v[98:113], v[216:219], v[156:159], v[98:113]
	v_exp_f32_e32 v183, v114
	ds_read_b64_tr_b16 v[130:131], v193 offset:59392
	ds_read_b64_tr_b16 v[132:133], v193 offset:59904
	v_exp_f32_e32 v215, v115
	ds_read_b128 v[142:145], v194 offset:4608
	v_add_f32_e32 v114, v183, v182
	v_cvt_pk_bf16_f32 v168, v223, v229
	v_mfma_f32_32x32x16_bf16 v[18:33], v[172:175], v[134:137], v[18:33]
	v_add_f32_e32 v114, v215, v114
	v_cvt_pk_bf16_f32 v169, v224, v225
	v_mfma_f32_32x32x16_bf16 v[50:65], v[172:175], v[138:141], v[50:65]
	v_exp_f32_e32 v182, v116
	ds_read_b64_tr_b16 v[134:135], v193 offset:63488
	ds_read_b64_tr_b16 v[136:137], v193 offset:64000
	v_exp_f32_e32 v216, v117
	v_cvt_pk_bf16_f32 v170, v195, v213
	v_add_f32_e32 v114, v182, v114
	v_cvt_pk_bf16_f32 v171, v180, v181
	v_add_f32_e32 v114, v216, v114
	s_waitcnt lgkmcnt(2)
	v_mfma_f32_32x32x16_bf16 v[66:81], v[142:145], v[156:159], v[66:81]
	v_exp_f32_e32 v142, v118
	ds_read_b64_tr_b16 v[138:139], v193 offset:27648
	ds_read_b64_tr_b16 v[140:141], v193 offset:28160
	v_exp_f32_e32 v143, v119
	ds_read_b128 v[116:119], v194 offset:6144
	v_add_f32_e32 v114, v142, v114
	v_add_f32_e32 v114, v143, v114
	v_mfma_f32_32x32x16_bf16 v[34:49], v[172:175], v[130:133], v[34:49]
	s_waitcnt lgkmcnt(3)
	v_mfma_f32_32x32x16_bf16 v[2:17], v[172:175], v[134:137], v[2:17]
	v_exp_f32_e32 v144, v120
	ds_read_b64_tr_b16 v[130:131], v193 offset:31744
	ds_read_b64_tr_b16 v[132:133], v193 offset:32256
	v_exp_f32_e32 v145, v121
	v_add_f32_e32 v114, v144, v114
	v_add_f32_e32 v172, v145, v114
	s_waitcnt lgkmcnt(2)
	v_mfma_f32_32x32x16_bf16 v[98:113], v[116:119], v[160:163], v[98:113]
	v_exp_f32_e32 v114, v122
	ds_read_b64_tr_b16 v[134:135], v193 offset:60416
	ds_read_b64_tr_b16 v[136:137], v193 offset:60928
	v_exp_f32_e32 v115, v123
	ds_read_b128 v[118:121], v194 offset:6656
	v_add_f32_e32 v116, v114, v172
	v_cvt_pk_bf16_f32 v172, v183, v215
	v_mfma_f32_32x32x16_bf16 v[18:33], v[176:179], v[138:141], v[18:33]
	v_add_f32_e32 v180, v115, v116
	v_cvt_pk_bf16_f32 v173, v182, v216
	s_waitcnt lgkmcnt(3)
	v_mfma_f32_32x32x16_bf16 v[50:65], v[176:179], v[130:133], v[50:65]
	v_exp_f32_e32 v116, v124
	v_exp_f32_e32 v117, v125
	ds_read_b64_tr_b16 v[122:123], v193 offset:64512
	ds_read_b64_tr_b16 v[124:125], v193 offset:65024
	v_cvt_pk_bf16_f32 v174, v142, v143
	v_add_f32_e32 v138, v116, v180
	v_add_f32_e32 v138, v117, v138
	v_cvt_pk_bf16_f32 v175, v144, v145
	s_waitcnt lgkmcnt(2)
	v_mfma_f32_32x32x16_bf16 v[66:81], v[118:121], v[160:163], v[66:81]
	v_exp_f32_e32 v118, v126
	v_exp_f32_e32 v119, v127
	v_add_f32_e32 v120, v118, v138
	v_add_f32_e32 v126, v119, v120
	v_mfma_f32_32x32x16_bf16 v[34:49], v[176:179], v[134:137], v[34:49]
	s_waitcnt lgkmcnt(0)
	v_mfma_f32_32x32x16_bf16 v[2:17], v[176:179], v[122:125], v[2:17]
	v_exp_f32_e32 v120, v128
	v_exp_f32_e32 v121, v129
	v_add_f32_e32 v122, v120, v126
	v_add_f32_e32 v122, v121, v122
	s_cmp_lg_u64 s[4:5], 0
	s_cbranch_scc1 .Lattn_rare_m1_b5

.LBB0_886:
	s_mulk_i32 s50, 0x6000
	s_sub_i32 s4, s25, s50
	s_add_i32 s4, s14, s4
	s_addk_i32 s4, 0xc000
	s_mov_b32 m0, s4
	v_lshl_add_u64 v[68:69], v[192:193], 0, s[44:45]
	global_load_lds_dwordx4 v[68:69], off
	s_andn2_b64 vcc, exec, s[76:77]
	s_cbranch_vccz .LBB0_869
	s_branch .LBB0_870
